# hgrn per-row RMS reduction: 16 serialized ds_bpermute hops replaced by DPP row-op adds (bit-identical butterfly), single ds_write_b128
# speedup vs baseline: 1.0007x; 1.0007x over previous
; __device__ __forceinline__ void item_hgrn(const Params& p, int l, int sidx) {
;     ...
; #pragma unroll
;         for (int j = 0; j < 4; ++j) {
;           int trow = tt * 16 + fq * 4 + j, scol = st * 16 + fr;
;           float v = (scol <= trow) ? pa[j] : 0.f;
;           Ps[trow * 72 + scol] = f2bf(v);
;         }
;       }
;     }
;     __syncthreads();
;     f32x4 oacc[4];
;     const int tt = wid & 3, dvh = wid >> 2;
;     {
; #pragma unroll
;       for (int n = 0; n < 4; ++n) oacc[n] = f32x4{0.f, 0.f, 0.f, 0.f};
; #pragma unroll
;       for (int ks = 0; ks < 2; ++ks) {
;         bf16x8 a = *reinterpret_cast<const bf16x8*>(Ps + (tt * 16 + fr) * 72 + ks * 32 + fq * 8);
; #pragma unroll
;         for (int n = 0; n < 4; ++n) {
;           bf16x8 bb = *reinterpret_cast<const bf16x8*>(VTs + (dvh * 64 + n * 16 + fr) * 72 + ks * 32 + fq * 8);
;           oacc[n] = __builtin_amdgcn_mfma_f32_16x16x32_bf16(a, bb, oacc[n], 0, 0, 0);
;         }
;       }
; #pragma unroll
;       for (int ks = 0; ks < 4; ++ks) {
;         bf16x8 a = *reinterpret_cast<const bf16x8*>(Qs + (tt * 16 + fr) * 136 + ks * 32 + fq * 8);
; #pragma unroll
;         for (int n = 0; n < 4; ++n) {
;           bf16x8 bb = *reinterpret_cast<const bf16x8*>(SpT + (dvh * 64 + n * 16 + fr) * 136 + ks * 32 + fq * 8);
;           oacc[n] = __builtin_amdgcn_mfma_f32_16x16x32_bf16(a, bb, oacc[n], 0, 0, 0);
;         }
;       }
.LBB0_816:
	s_nop 7
	v_cndmask_b32_e64 v40, v40, 0, s[20:21]
	v_bfe_u32 v44, v40, 16, 1
	v_add3_u32 v40, v40, v44, s80
	ds_write_b16_d16_hi v149, v40
	v_cndmask_b32_e64 v40, v41, 0, s[22:23]
	v_bfe_u32 v41, v40, 16, 1
	v_add3_u32 v40, v40, v41, s80
	ds_write_b16_d16_hi v150, v40
	v_cndmask_b32_e64 v40, v42, 0, s[24:25]
	v_bfe_u32 v41, v40, 16, 1
	v_add3_u32 v40, v40, v41, s80
	ds_write_b16_d16_hi v151, v40
	v_cndmask_b32_e64 v40, v43, 0, s[26:27]
	v_bfe_u32 v41, v40, 16, 1
	v_add3_u32 v40, v40, v41, s80
	ds_write_b16_d16_hi v152, v40
	s_waitcnt lgkmcnt(0)
	s_barrier
	ds_read_b128 v[40:43], v83
	ds_read_b128 v[44:47], v166 offset:53248
	ds_read_b128 v[48:51], v166 offset:55552
	ds_read_b128 v[52:55], v166 offset:57856
	ds_read_b128 v[56:59], v166 offset:60160
	s_waitcnt lgkmcnt(3)
	v_mfma_f32_16x16x32_bf16 v[44:47], v[40:43], v[44:47], 0
	v_xor_b32_e32 v207, 8, v215
	s_waitcnt lgkmcnt(2)
	v_mfma_f32_16x16x32_bf16 v[48:51], v[40:43], v[48:51], 0
	s_waitcnt lgkmcnt(1)
	v_mfma_f32_16x16x32_bf16 v[52:55], v[40:43], v[52:55], 0
	s_waitcnt lgkmcnt(0)
	v_mfma_f32_16x16x32_bf16 v[40:43], v[40:43], v[56:59], 0
	ds_read_b128 v[56:59], v83 offset:64
	ds_read_b128 v[218:221], v166 offset:53312
	s_waitcnt lgkmcnt(0)
	v_mfma_f32_16x16x32_bf16 v[44:47], v[56:59], v[218:221], v[44:47]
	ds_read_b128 v[218:221], v166 offset:55616
	s_waitcnt lgkmcnt(0)
	v_mfma_f32_16x16x32_bf16 v[48:51], v[56:59], v[218:221], v[48:51]
	ds_read_b128 v[218:221], v166 offset:57920
	s_waitcnt lgkmcnt(0)
	v_mfma_f32_16x16x32_bf16 v[52:55], v[56:59], v[218:221], v[52:55]
	ds_read_b128 v[218:221], v166 offset:60224
	s_waitcnt lgkmcnt(0)
	v_mfma_f32_16x16x32_bf16 v[40:43], v[56:59], v[218:221], v[40:43]
	ds_read_b128 v[56:59], v101
	ds_read_b128 v[218:221], v167
	s_waitcnt lgkmcnt(0)
	v_mfma_f32_16x16x32_bf16 v[44:47], v[56:59], v[218:221], v[44:47]
	ds_read_b128 v[218:221], v167 offset:4352
	s_waitcnt lgkmcnt(0)
	v_mfma_f32_16x16x32_bf16 v[48:51], v[56:59], v[218:221], v[48:51]
	ds_read_b128 v[218:221], v167 offset:8704
	s_waitcnt lgkmcnt(0)
	v_mfma_f32_16x16x32_bf16 v[52:55], v[56:59], v[218:221], v[52:55]
	ds_read_b128 v[218:221], v167 offset:13056
	s_waitcnt lgkmcnt(0)
	v_mfma_f32_16x16x32_bf16 v[40:43], v[56:59], v[218:221], v[40:43]
	ds_read_b128 v[56:59], v101 offset:64
	ds_read_b128 v[218:221], v167 offset:64
	s_waitcnt lgkmcnt(0)
	v_mfma_f32_16x16x32_bf16 v[44:47], v[56:59], v[218:221], v[44:47]
	ds_read_b128 v[218:221], v167 offset:4416
	s_waitcnt lgkmcnt(0)
	v_mfma_f32_16x16x32_bf16 v[48:51], v[56:59], v[218:221], v[48:51]
	ds_read_b128 v[218:221], v167 offset:8768
	s_waitcnt lgkmcnt(0)
	v_mfma_f32_16x16x32_bf16 v[52:55], v[56:59], v[218:221], v[52:55]
	ds_read_b128 v[218:221], v167 offset:13120
	s_waitcnt lgkmcnt(0)
	v_mfma_f32_16x16x32_bf16 v[40:43], v[56:59], v[218:221], v[40:43]
	ds_read_b128 v[56:59], v101 offset:128
	ds_read_b128 v[218:221], v167 offset:128
	s_waitcnt lgkmcnt(0)
	v_mfma_f32_16x16x32_bf16 v[44:47], v[56:59], v[218:221], v[44:47]
	ds_read_b128 v[218:221], v167 offset:4480
	s_waitcnt lgkmcnt(0)
	v_mfma_f32_16x16x32_bf16 v[48:51], v[56:59], v[218:221], v[48:51]
	ds_read_b128 v[218:221], v167 offset:8832
	s_waitcnt lgkmcnt(0)
	v_mfma_f32_16x16x32_bf16 v[52:55], v[56:59], v[218:221], v[52:55]
	ds_read_b128 v[218:221], v167 offset:13184
	s_waitcnt lgkmcnt(0)
	v_mfma_f32_16x16x32_bf16 v[56:59], v[56:59], v[218:221], v[40:43]
	ds_read_b128 v[218:221], v101 offset:192
	s_nop 1
	ds_read_b128 v[40:43], v167 offset:192
	s_waitcnt lgkmcnt(0)
	v_mfma_f32_16x16x32_bf16 v[40:43], v[218:221], v[40:43], v[44:47]
	s_nop 2
	ds_read_b128 v[44:47], v167 offset:4544
	s_waitcnt lgkmcnt(0)
	v_mfma_f32_16x16x32_bf16 v[44:47], v[218:221], v[44:47], v[48:51]
	s_nop 2
	ds_read_b128 v[48:51], v167 offset:8896
	s_waitcnt lgkmcnt(0)
	v_mfma_f32_16x16x32_bf16 v[48:51], v[218:221], v[48:51], v[52:55]
	s_nop 2
	ds_read_b128 v[52:55], v167 offset:13248
	s_waitcnt lgkmcnt(0)
; __device__ __forceinline__ void item_hgrn(const Params& p, int l, int sidx) {
;     ...
; #pragma unroll
;       for (int j = 0; j < 4; ++j) {
;         float ss = 0.f;
; #pragma unroll
;         for (int n = 0; n < 4; ++n) ss += oacc[n][j] * oacc[n][j];
;         ss += __shfl_xor(ss, 1); ss += __shfl_xor(ss, 2); ss += __shfl_xor(ss, 4); ss += __shfl_xor(ss, 8);
;         if (fr == 0) ssq[dvh * 64 + tt * 16 + fq * 4 + j] = ss;
;       }
;     }
;     {
; #pragma unroll
;       for (int ks = 0; ks < 2; ++ks) {
;         bf16x8 a = *reinterpret_cast<const bf16x8*>(KTs + (16 * wid + fr) * 72 + ks * 32 + fq * 8);
; #pragma unroll
;         for (int n = 0; n < 8; ++n) {
;           bf16x8 bb = *reinterpret_cast<const bf16x8*>(VTs + (n * 16 + fr) * 72 + ks * 32 + fq * 8);
;           S[n] = __builtin_amdgcn_mfma_f32_16x16x32_bf16(a, bb, S[n], 0, 0, 0);
;         }
;       }
	v_mfma_f32_16x16x32_bf16 v[52:55], v[218:221], v[52:55], v[56:59]
	s_nop 2
	v_mul_f32_e32 v56, v44, v44
	v_mul_f32_e32 v57, v45, v45
	v_mul_f32_e32 v58, v46, v46
	v_mul_f32_e32 v59, v47, v47
	v_fmac_f32_e32 v56, v40, v40
	v_fmac_f32_e32 v57, v41, v41
	v_fmac_f32_e32 v58, v42, v42
	v_fmac_f32_e32 v59, v43, v43
	v_fmac_f32_e32 v56, v48, v48
	v_fmac_f32_e32 v57, v49, v49
	v_fmac_f32_e32 v58, v50, v50
	v_fmac_f32_e32 v59, v51, v51
	v_fmac_f32_e32 v56, v52, v52
	v_fmac_f32_e32 v57, v53, v53
	v_fmac_f32_e32 v58, v54, v54
	v_fmac_f32_e32 v59, v55, v55
	v_add_f32_dpp v56, v56, v56 quad_perm:[1,0,3,2] row_mask:0xf bank_mask:0xf
	v_add_f32_dpp v57, v57, v57 quad_perm:[1,0,3,2] row_mask:0xf bank_mask:0xf
	v_add_f32_dpp v58, v58, v58 quad_perm:[1,0,3,2] row_mask:0xf bank_mask:0xf
	v_add_f32_dpp v59, v59, v59 quad_perm:[1,0,3,2] row_mask:0xf bank_mask:0xf
	v_add_f32_dpp v56, v56, v56 quad_perm:[2,3,0,1] row_mask:0xf bank_mask:0xf
	v_add_f32_dpp v57, v57, v57 quad_perm:[2,3,0,1] row_mask:0xf bank_mask:0xf
	v_add_f32_dpp v58, v58, v58 quad_perm:[2,3,0,1] row_mask:0xf bank_mask:0xf
	v_add_f32_dpp v59, v59, v59 quad_perm:[2,3,0,1] row_mask:0xf bank_mask:0xf
	v_add_f32_dpp v56, v56, v56 row_half_mirror row_mask:0xf bank_mask:0xf
	v_add_f32_dpp v57, v57, v57 row_half_mirror row_mask:0xf bank_mask:0xf
	v_add_f32_dpp v58, v58, v58 row_half_mirror row_mask:0xf bank_mask:0xf
	v_add_f32_dpp v59, v59, v59 row_half_mirror row_mask:0xf bank_mask:0xf
	v_add_f32_dpp v56, v56, v56 row_mirror row_mask:0xf bank_mask:0xf
	v_add_f32_dpp v57, v57, v57 row_mirror row_mask:0xf bank_mask:0xf
	v_add_f32_dpp v58, v58, v58 row_mirror row_mask:0xf bank_mask:0xf
	v_add_f32_dpp v59, v59, v59 row_mirror row_mask:0xf bank_mask:0xf
	v_add_u32_e32 v207, s87, v96
	s_and_saveexec_b64 s[2:3], s[10:11]
	ds_write_b128 v207, v[56:59]
	s_or_b64 exec, exec, s[2:3]
	s_waitcnt lgkmcnt(0)
	ds_read_b128 v[56:59], v84 offset:34816
	ds_read_b128 v[218:221], v168 offset:53248
	v_cmp_gt_u32_e32 vcc, s86, v206
	s_waitcnt lgkmcnt(0)
	v_mfma_f32_16x16x32_bf16 v[8:11], v[56:59], v[218:221], v[8:11]
	ds_read_b128 v[218:221], v169 offset:53248
	s_waitcnt lgkmcnt(0)
	v_mfma_f32_16x16x32_bf16 v[12:15], v[56:59], v[218:221], v[12:15]
	ds_read_b128 v[218:221], v170 offset:53248
	s_waitcnt lgkmcnt(0)
	v_mfma_f32_16x16x32_bf16 v[16:19], v[56:59], v[218:221], v[16:19]
	ds_read_b128 v[218:221], v171 offset:53248
	s_waitcnt lgkmcnt(0)
	v_mfma_f32_16x16x32_bf16 v[20:23], v[56:59], v[218:221], v[20:23]
	ds_read_b128 v[218:221], v172 offset:53248
	s_waitcnt lgkmcnt(0)
	v_mfma_f32_16x16x32_bf16 v[218:221], v[56:59], v[218:221], v[24:27]
	s_nop 2
	ds_read_b128 v[24:27], v173 offset:53248
	s_waitcnt lgkmcnt(0)
	v_mfma_f32_16x16x32_bf16 v[222:225], v[56:59], v[24:27], v[28:31]
	ds_read_b128 v[24:27], v174 offset:53248
	s_waitcnt lgkmcnt(0)
	v_mfma_f32_16x16x32_bf16 v[226:229], v[56:59], v[24:27], v[32:35]
	ds_read_b128 v[24:27], v175 offset:53248
	s_waitcnt lgkmcnt(0)
	v_mfma_f32_16x16x32_bf16 v[36:39], v[56:59], v[24:27], v[36:39]
	ds_read_b128 v[230:233], v84 offset:34880
	ds_read_b128 v[24:27], v168 offset:53312
	s_waitcnt lgkmcnt(0)
	v_mfma_f32_16x16x32_bf16 v[8:11], v[230:233], v[24:27], v[8:11]
	ds_read_b128 v[24:27], v169 offset:53312
	s_waitcnt lgkmcnt(0)
	v_mfma_f32_16x16x32_bf16 v[12:15], v[230:233], v[24:27], v[12:15]
	ds_read_b128 v[24:27], v170 offset:53312
	s_waitcnt lgkmcnt(0)
	v_mfma_f32_16x16x32_bf16 v[16:19], v[230:233], v[24:27], v[16:19]
	ds_read_b128 v[24:27], v171 offset:53312
	s_waitcnt lgkmcnt(0)
	v_mfma_f32_16x16x32_bf16 v[24:27], v[230:233], v[24:27], v[20:23]
	s_nop 2
	ds_read_b128 v[20:23], v172 offset:53312
	s_waitcnt lgkmcnt(0)
	v_mfma_f32_16x16x32_bf16 v[28:31], v[230:233], v[20:23], v[218:221]
	ds_read_b128 v[20:23], v173 offset:53312
	s_waitcnt lgkmcnt(0)
	v_mfma_f32_16x16x32_bf16 v[32:35], v[230:233], v[20:23], v[222:225]
	ds_read_b128 v[20:23], v174 offset:53312
	s_waitcnt lgkmcnt(0)
	v_mfma_f32_16x16x32_bf16 v[56:59], v[230:233], v[20:23], v[226:229]
	ds_read_b128 v[20:23], v175 offset:53312
	s_waitcnt lgkmcnt(0)
	v_mfma_f32_16x16x32_bf16 v[20:23], v[230:233], v[20:23], v[36:39]
	s_nop 2
	v_add_u32_e32 v36, s88, v96
	ds_read_b128 v[36:39], v36
	s_waitcnt lgkmcnt(0)
	s_barrier
	s_and_saveexec_b64 s[28:29], vcc
	s_cbranch_execnz .LBB0_828
	s_or_b64 exec, exec, s[28:29]
	v_cmp_gt_u32_e32 vcc, s86, v201
	s_and_saveexec_b64 s[28:29], vcc
	s_cbranch_execnz .LBB0_829
